# attention: one static s_setprio 1 for waves 4-7 at each unit prologue (younger half of every SIMD pair)
# speedup vs baseline: 1.0105x; 1.0105x over previous
; #define LAS __attribute__((address_space(3)))
;     ...
;     const int tid = tid_, lane = tid & 63, wid = __builtin_amdgcn_readfirstlane(tid >> 6), r32 = lane & 31, hi = lane >> 5;
;     const size_t rowbase = (size_t)b * SEQ;
;     const int q0 = qb * 256, qw = q0 + wid * 32;
;     bf16x8 qr[4];
;     { const bf16* qp = UGQ + (rowbase + qw + r32) * 2048 + 1024 + h * HD + hi * 8;
; #pragma unroll
;       for (int d0 = 0; d0 < 4; ++d0) qr[d0] = *(const bf16x8*)(qp + d0 * 16); }
;     f32x16 o0, o1;
; #pragma unroll
;     for (int r = 0; r < 16; ++r) { o0[r] = 0.f; o1[r] = 0.f; }
;     float C = 1.f; int alive = 1;
;     volatile LAS unsigned* aflag = (volatile LAS unsigned*)(lds + RING_BYTES);
;     const int NT = 4 * (qb + 1);
;     const int lkey = lane, lch = wid;
;     const int kk = lkey & 31, slot = (lkey & 32) | (8 * ((kk >> 2) & 3) + 4 * (kk >> 4) + (kk & 3));
;     const bf16* kg = Kb + (rowbase + lkey) * 1024 + h * HD + lch * 8;
;     const bf16* vg = Vb + (rowbase + lkey) * 1024 + h * HD + lch * 8;
;     u32x4 kreg, vreg;
;     kreg = *(const u32x4*)(kg + (size_t)(NT - 1) * 64 * 1024); vreg = *(const u32x4*)(vg + (size_t)(NT - 1) * 64 * 1024);
;     ...
;     AT_WRITE(0);
;     __syncthreads();
;     ...
;         const u32x4 gw_ = *(const u32x4*)(GBb + tok * 1024 + h * HD + ch * 8);
.LBB0_457:
	s_xor_b64 s[28:29], s[4:5], -1
	s_and_b64 s[4:5], s[4:5], exec
	v_readlane_b32 s1, v255, 48
	v_mov_b32_e32 v104, v232
	s_cselect_b32 s6, s1, s0
	v_readlane_b32 s12, v254, 58
	v_readfirstlane_b32 s1, v104
	s_ashr_i32 s33, s1, 6
	s_lshl_b32 s1, s6, 8
	s_lshl_b32 s24, s33, 5
	s_add_i32 s24, s24, s1
	s_ashr_i32 s4, s24, 31
	s_add_u32 s10, s18, s24
	v_and_b32_e32 v106, 31, v104
	s_addc_u32 s11, s19, s4
	s_cmp_lt_u32 s33, 4
	s_cbranch_scc1 .Lattn_prio_skip
	s_setprio 1
.Lattn_prio_skip:
	v_or_b32_e32 v0, s10, v106
	v_mov_b32_e32 v1, s11
	v_bfe_u32 v4, v104, 5, 1
	v_lshlrev_b64 v[0:1], 12, v[0:1]
	v_lshl_add_u64 v[0:1], s[30:31], 0, v[0:1]
	v_lshlrev_b32_e32 v64, 4, v4
	v_lshl_add_u64 v[0:1], v[0:1], 0, v[64:65]
	global_load_dwordx4 v[66:69], v[0:1], off offset:2048
	global_load_dwordx4 v[70:73], v[0:1], off offset:2080
	global_load_dwordx4 v[74:77], v[0:1], off offset:2112
	global_load_dwordx4 v[78:81], v[0:1], off offset:2144
	v_lshlrev_b32_e32 v0, 1, v104
	v_lshrrev_b32_e32 v1, 2, v104
	v_and_b32_e32 v105, 63, v104
	v_lshlrev_b32_e32 v114, 3, v104
	v_lshrrev_b32_e32 v116, 3, v105
	v_and_b32_e32 v114, 56, v114
	v_or_b32_e32 v116, s10, v116
	v_mov_b32_e32 v117, s11
	v_lshlrev_b32_e32 v114, 1, v114
	v_mov_b32_e32 v115, 0
	v_lshlrev_b64 v[116:117], 11, v[116:117]
	v_lshl_add_u64 v[114:115], s[14:15], 0, v[114:115]
	s_mov_b64 s[100:101], 0x4000
	v_lshl_add_u64 v[114:115], v[114:115], 0, v[116:117]
	global_load_dwordx4 v[128:131], v[114:115], off
	v_lshl_add_u64 v[116:117], v[114:115], 0, s[100:101]
	global_load_dwordx4 v[132:135], v[116:117], off
	v_lshl_add_u64 v[116:117], s[100:101], 1, v[114:115]
	global_load_dwordx4 v[136:139], v[116:117], off
	v_lshl_add_u64 v[116:117], v[116:117], 0, s[100:101]
	global_load_dwordx4 v[164:167], v[116:117], off
	v_and_b32_e32 v0, 24, v0
	v_and_b32_e32 v1, 4, v1
	v_and_b32_e32 v2, 35, v104
	v_or3_b32 v5, v2, v1, v0
	v_or_b32_e32 v0, s18, v105
	v_mov_b32_e32 v1, s19
	v_readlane_b32 s4, v255, 49
	v_lshlrev_b64 v[0:1], 11, v[0:1]
	v_readlane_b32 s5, v255, 50
	s_lshl_b32 s7, s6, 19
	v_readlane_b32 s13, v254, 59
	v_lshl_add_u64 v[2:3], s[4:5], 0, v[0:1]
	s_lshl_b32 s4, s33, 3
	s_ashr_i32 s5, s4, 31
	s_lshl_b64 s[4:5], s[4:5], 1
	v_lshl_add_u64 v[0:1], s[8:9], 0, v[0:1]
	v_lshl_add_u64 v[2:3], v[2:3], 0, s[4:5]
	v_lshl_add_u64 v[0:1], v[0:1], 0, s[4:5]
	s_mov_b32 s21, s13
	s_or_b32 s20, s7, 0x60000
	v_lshl_add_u64 v[2:3], v[2:3], 0, s[20:21]
	v_lshl_add_u64 v[0:1], v[0:1], 0, s[20:21]
	global_load_dwordx4 v[82:85], v[2:3], off
	global_load_dwordx4 v[86:89], v[0:1], off
	s_lshl_b32 s25, s6, 2
	s_lshl_b32 s6, s33, 10
	v_writelane_b32 v254, s12, 58
	s_add_i32 s20, s6, 0
	s_mul_i32 s6, s33, 0x480
	v_writelane_b32 v254, s13, 59
	s_add_i32 s6, s6, 0
	v_lshl_add_u32 v108, v105, 1, s6
	s_lshl_b32 s6, s33, 2
	v_readlane_b32 s12, v254, 57
	s_add_i32 s25, s25, 4
	s_add_i32 s26, s12, s6
	v_lshlrev_b32_e32 v0, 10, v4
	v_lshlrev_b32_e32 v1, 4, v106
	v_add3_u32 v111, 0, v0, v1
	v_mul_u32_u24_e32 v0, 0x90, v106
	v_and_b32_e32 v1, 32, v104
	s_add_u32 s4, s4, s7
	v_add3_u32 v112, 0, v0, v1
	v_lshlrev_b32_e32 v0, 11, v105
	v_mov_b32_e32 v1, v65
	s_addc_u32 s5, s5, 0
	v_lshl_add_u64 v[0:1], s[4:5], 0, v[0:1]
	v_mov_b32_e32 v14, v65
	v_mov_b32_e32 v15, v65
	v_lshl_add_u32 v107, v5, 4, s20
	v_lshl_add_u64 v[90:91], s[34:35], 0, v[0:1]
	v_lshl_add_u64 v[92:93], s[2:3], 0, v[0:1]
	v_mov_b32_e32 v0, v65
	v_mov_b32_e32 v1, v65
	v_mov_b32_e32 v2, v65
	v_mov_b32_e32 v3, v65
	v_mov_b32_e32 v4, v65
	v_mov_b32_e32 v5, v65
	v_mov_b32_e32 v6, v65
	v_mov_b32_e32 v7, v65
	v_mov_b32_e32 v8, v65
	v_mov_b32_e32 v9, v65
	v_mov_b32_e32 v10, v65
	v_mov_b32_e32 v11, v65
	v_mov_b32_e32 v12, v65
	v_mov_b32_e32 v13, v65
	v_mov_b64_e32 v[30:31], v[14:15]
	v_or_b32_e32 v109, s24, v106
	v_lshl_add_u32 v110, v105, 2, s12
	v_cmp_gt_u32_e64 s[36:37], 32, v105
	s_mov_b32 s6, 0
	v_cmp_eq_u32_e64 s[38:39], 0, v105
	v_cmp_gt_u32_e64 s[40:41], 8, v105
	s_or_b32 s27, s1, 0xc0
	v_mov_b32_e32 v95, 1.0
	v_mov_b32_e32 v32, 1
	v_mov_b64_e32 v[28:29], v[12:13]
	v_mov_b64_e32 v[26:27], v[10:11]
	v_mov_b64_e32 v[24:25], v[8:9]
	v_mov_b64_e32 v[22:23], v[6:7]
	v_mov_b64_e32 v[20:21], v[4:5]
	v_mov_b64_e32 v[18:19], v[2:3]
	v_mov_b64_e32 v[16:17], v[0:1]
	s_waitcnt vmcnt(1)
	ds_write_b128 v107, v[82:85]
	s_waitcnt vmcnt(0)
	ds_write_b16 v108, v86 offset:16384
	ds_write_b16_d16_hi v108, v86 offset:16528
	ds_write_b16 v108, v87 offset:16672
	ds_write_b16_d16_hi v108, v87 offset:16816
	ds_write_b16 v108, v88 offset:16960
	ds_write_b16_d16_hi v108, v88 offset:17104
	ds_write_b16 v108, v89 offset:17248
	ds_write_b16_d16_hi v108, v89 offset:17392
	s_waitcnt lgkmcnt(0)
	s_barrier
	s_cmpk_eq_i32 s27, 0xffc0
	s_cbranch_scc0 .LBB0_459
